# MLA: score accumulators start from a persistent -boff register block (no per-tile init moves), SALU tile-skip test; DIFF fast path rebuilds its init block only when the reference max changed
# speedup vs baseline: 1.0711x; 1.0057x over previous
; #define LAS __attribute__((address_space(3)))
; __device__ __forceinline__ float max3f(float a, float b, float c) { return __builtin_fmaxf(__builtin_fmaxf(a, b), c); }
; __device__ __forceinline__ void softmax_tile(f32x16& s0, f32x16& s1, SM& st, float boff, ldsp_t vb, int hh, int r) {
;     ...
;   float zmax = max3f(s0[0], s0[1], s0[2]);
; #pragma unroll
;   for (int k = 0; k < 6; ++k) zmax = max3f(zmax, s0[3 + 2 * k], s0[4 + 2 * k]);
;   zmax = max3f(zmax, s0[15], s1[0]);
; #pragma unroll
;   for (int k = 0; k < 7; ++k) zmax = max3f(zmax, s1[1 + 2 * k], s1[2 + 2 * k]);
;   zmax = fmaxf(zmax, s1[15]);
; #pragma unroll
;   for (int i = 0; i < 16; ++i) { s0[i] = __builtin_amdgcn_exp2f(s0[i]); s1[i] = __builtin_amdgcn_exp2f(s1[i]); }
; template <int MODE>
; __device__ __forceinline__ void attn_item(const Params& P, int layer, int b, int h, int map, int qb) {
;     ...
;   auto qk = [&](f32x16& s0, f32x16& s1, float& boff, int bufi, int t) {
;     const ldsp_t kbuf = lds + bufi * KBUF;
;     __builtin_amdgcn_s_setprio(1);
;     boff = sa.m > -1e29f ? sa.m : 0.f;
;     const float init = ((MODE == 1 && !lookf(t)) ? cfar : 0.f) - boff;
; #pragma unroll
;     for (int q = 0; q < 16; ++q) { s0[q] = init; s1[q] = init; }
; #pragma unroll
;     for (int s = 0; s < NST; ++s) {
;       const bf16x8 a0 = *(LAS const bf16x8*)(kbuf + pr * KSTR + s * 32 + hh * 16);
;       const bf16x8 a1 = *(LAS const bf16x8*)(kbuf + (32 + pr) * KSTR + s * 32 + hh * 16);
;       s0 = __builtin_amdgcn_mfma_f32_32x32x16_bf16(a0, qf[s], s0, 0, 0, 0);
;       s1 = __builtin_amdgcn_mfma_f32_32x32x16_bf16(a1, qf[s], s1, 0, 0, 0);
;     }
.Ldf_fast:
	s_mul_i32 s6, s78, 0x1400
	s_or_b32 s7, s78, 1
	s_mul_i32 s2, s7, 0x1400
	v_add_u32_e32 v160, s6, v227
	v_add_u32_e32 v161, s2, v227
	ds_read_b128 v[178:181], v160
	ds_read_b128 v[182:185], v160 offset:2560
	ds_read_b128 v[186:189], v160 offset:32
	ds_read_b128 v[190:193], v160 offset:2592
	ds_read_b128 v[194:197], v161
	ds_read_b128 v[198:201], v161 offset:2560
	ds_read_b128 v[202:205], v161 offset:32
	ds_read_b128 v[206:209], v161 offset:2592
	v_cmp_lt_f32_e32 vcc, s87, v177
	s_mul_i32 s6, s78, 0x2400
	s_mul_i32 s7, s7, 0x2400
	v_cndmask_b32_e32 v176, 0, v177, vcc
	s_cmp_eq_u32 s48, 2
	s_cbranch_scc1 .Ldf_reinit
	v_cmp_neq_f32_e32 vcc, v176, v252
	s_cbranch_vccz .Ldf_noinit
.Ldf_reinit:
	v_mov_b32_e32 v252, v176
	v_sub_f32_e32 v230, v221, v176
	v_mov_b32_e32 v231, v230
	v_mov_b32_e32 v232, v230
	v_mov_b32_e32 v233, v230
	v_mov_b32_e32 v234, v230
	v_mov_b32_e32 v235, v230
	v_mov_b32_e32 v236, v230
	v_mov_b32_e32 v237, v230
	v_mov_b32_e32 v238, v230
	v_mov_b32_e32 v239, v230
	v_mov_b32_e32 v240, v230
	v_mov_b32_e32 v241, v230
	v_mov_b32_e32 v242, v230
	v_mov_b32_e32 v243, v230
	v_mov_b32_e32 v244, v230
	v_mov_b32_e32 v245, v230
.Ldf_noinit:
	v_add3_u32 v158, s6, v224, v0
	v_add3_u32 v246, s7, v224, v0
	s_waitcnt lgkmcnt(7)
	v_mfma_f32_32x32x16_bf16 v[50:65], v[178:181], v[102:105], v[230:245]
	s_waitcnt lgkmcnt(6)
	v_mfma_f32_32x32x16_bf16 v[34:49], v[182:185], v[102:105], v[230:245]
	s_waitcnt lgkmcnt(5)
	v_mfma_f32_32x32x16_bf16 v[50:65], v[186:189], v[98:101], v[50:65]
	s_waitcnt lgkmcnt(4)
	v_mfma_f32_32x32x16_bf16 v[34:49], v[190:193], v[98:101], v[34:49]
	ds_read_b128 v[146:149], v158 offset:20480
	ds_read_b128 v[142:145], v158 offset:20512
	ds_read_b128 v[150:153], v158 offset:25088
	ds_read_b128 v[138:141], v158 offset:25120
	ds_read_b128 v[134:137], v158 offset:20544
	ds_read_b128 v[126:129], v158 offset:20576
	ds_read_b128 v[130:133], v158 offset:25152
	ds_read_b128 v[122:125], v158 offset:25184
	s_waitcnt lgkmcnt(11)
	v_mfma_f32_32x32x16_bf16 v[82:97], v[194:197], v[102:105], v[230:245]
	s_waitcnt lgkmcnt(10)
	v_mfma_f32_32x32x16_bf16 v[66:81], v[198:201], v[102:105], v[230:245]
	v_max3_f32 v156, v50, v51, v52
	v_max3_f32 v156, v156, v53, v54
	v_max3_f32 v156, v156, v55, v56
	v_max3_f32 v156, v156, v57, v58
	v_max3_f32 v156, v156, v59, v60
	v_max3_f32 v156, v156, v61, v62
	v_max3_f32 v156, v156, v63, v64
	v_max3_f32 v156, v156, v65, v34
	v_max3_f32 v156, v156, v35, v36
	v_max3_f32 v156, v156, v37, v38
	v_max3_f32 v156, v156, v39, v40
	v_max3_f32 v156, v156, v41, v42
	v_max3_f32 v156, v156, v43, v44
	v_max3_f32 v156, v156, v45, v46
	v_max3_f32 v156, v156, v47, v48
	v_max_f32_e32 v156, v156, v49
	v_exp_f32_e32 v50, v50
	v_exp_f32_e32 v34, v34
	s_waitcnt lgkmcnt(9)
	v_mfma_f32_32x32x16_bf16 v[82:97], v[202:205], v[98:101], v[82:97]
	v_exp_f32_e32 v51, v51
	v_exp_f32_e32 v35, v35
	v_exp_f32_e32 v52, v52
	v_exp_f32_e32 v36, v36
	v_exp_f32_e32 v53, v53
	v_exp_f32_e32 v37, v37
	v_exp_f32_e32 v54, v54
	v_exp_f32_e32 v38, v38
	v_exp_f32_e32 v55, v55
	v_exp_f32_e32 v39, v39
	v_exp_f32_e32 v56, v56
	v_exp_f32_e32 v40, v40
	v_exp_f32_e32 v57, v57
	v_exp_f32_e32 v41, v41
	v_exp_f32_e32 v58, v58
	v_exp_f32_e32 v42, v42
	v_exp_f32_e32 v59, v59
	v_exp_f32_e32 v43, v43
	v_exp_f32_e32 v60, v60
	v_exp_f32_e32 v44, v44
	s_waitcnt lgkmcnt(8)
	v_mfma_f32_32x32x16_bf16 v[66:81], v[206:209], v[98:101], v[66:81]
	v_exp_f32_e32 v61, v61
	v_exp_f32_e32 v45, v45
	v_exp_f32_e32 v62, v62
	v_exp_f32_e32 v46, v46
	v_exp_f32_e32 v63, v63
	v_exp_f32_e32 v47, v47
	v_exp_f32_e32 v64, v64
	v_exp_f32_e32 v48, v48
	v_exp_f32_e32 v65, v65
	v_exp_f32_e32 v49, v49
	v_pk_add_f32 v[160:161], v[176:177], v[156:157]
	v_cmp_neq_f32_e64 s[4:5], v177, v176
	v_cmp_gt_f32_e32 vcc, v160, v161
	s_or_b64 vcc, s[4:5], vcc
	s_cbranch_vccnz .Ldf_slow_a

; #define LAS __attribute__((address_space(3)))
; template <int MODE>
; __device__ __forceinline__ void attn_item(const Params& P, int layer, int b, int h, int map, int qb) {
;     ...
;   const int eq0 = meta ? 0 : 64 + 256 * qb + 32 * w, e_q = eq0 + r;
;   const bool active = !meta || w == 0, qvalid = !meta || (w == 0 && r < 16);
;   const int posq = pos_of_e(e_q);
;   if (MODE != 0) { if (tid < 129) tab[tid] = P.rel_bias[T5B[tid] * 10 + bcol] * LOG2E; }
;   bf16x8 qf[NST];
; #pragma unroll
;   for (int s = 0; s < NST; ++s) qf[s] = qvalid ? *(const bf16x8*)(qp + (size_t)e_q * KLD + s * 16 + hh * 8) : (bf16x8){0, 0, 0, 0, 0, 0, 0, 0};
;   int tstart = 1, ntl;
;   if (meta) ntl = 1; else if (MODE == 2) { tstart = max(1, 4 * qb - 1); ntl = 4 * qb + 6 - tstart; } else ntl = 4 * qb + 5;
;   SM sa;
;   sa.m = NEG; sa.l = 0.f;
; #pragma unroll
;   for (int i = 0; i < 16; ++i) { sa.o0[i] = 0.f; sa.o1[i] = 0.f; }
;   if (MODE == 2) { sa.m = P.sinks[layer * 6 + h] * LOG2E; sa.l = hh == 0 ? 1.f : 0.f; }
;   float cfar = 0.f; if (MODE == 1) cfar = P.rel_bias[31 * 10 + bcol] * LOG2E;
;   struct Stage { u32x4 k[NLK], v; };
;   Stage stX, stY;
;   auto issue = [&](Stage& st, int t) {
; #pragma unroll
;     for (int u = 0; u < NLK; ++u) { int c = tid + 512 * u; if (c >= NKC) c -= (NKC % 512 == 0 ? 512 : NKC % 512);
;       const int row = c / CPR, cc = c % CPR; st.k[u] = *(const u32x4*)(kp + (size_t)(64 * t + row) * KLD + cc * 8); }
;     { const int row = tid >> 3, cc = tid & 7; st.v = *(const u32x4*)(vp + (size_t)row * E + 64 * t + cc * 8); }
;   };
;   auto commit = [&](const Stage& st, int bufi) {
; #pragma unroll
;     for (int u = 0; u < NLK; ++u) { int c = tid + 512 * u; if (c >= NKC) c -= (NKC % 512 == 0 ? 512 : NKC % 512);
;       const int row = c / CPR, cc = c % CPR; *(LAS u32x4*)(lds + bufi * KBUF + row * KSTR + cc * 16) = st.k[u]; }
;     { const int row = tid >> 3, cc = tid & 7; *(LAS u32x4*)(lds + 4 * KBUF + bufi * VBUF + row * 144 + cc * 16) = st.v; }
;   };
;   auto tile_of = [&](int i) { return i == 0 ? 0 : tstart + i - 1; };
;   auto skipf = [&](int t) { bool sk = !active; if (t > 0) { if (64 * t > eq0 + 31) sk = true; if (MODE == 2 && eq0 - (64 * t + 63) >= 128) sk = true; } return sk; };
;   const int pr = (r & 0x13) | ((r & 4) << 1) | ((r & 8) >> 1);
;   auto lookf = [&](int t) { return MODE != 0 && (t == 0 || MODE == 2 || (eq0 - (64 * t + 63) < 128)); };
.LBB0_1306:
	s_or_b64 exec, exec, s[4:5]
	v_add_u32_e32 v2, 0xffffff00, v5
	v_cmp_lt_i32_e32 vcc, s94, v5
	v_ashrrev_i32_e32 v45, 3, v5
	s_lshl_b32 s90, s76, 1
	v_cndmask_b32_e32 v2, v5, v2, vcc
	v_mul_hi_i32 v3, v2, s55
	v_lshrrev_b32_e32 v7, 31, v3
	v_ashrrev_i32_e32 v3, 1, v3
	v_add_u32_e32 v180, v3, v7
	v_mul_lo_u32 v3, v180, 12
	v_sub_u32_e32 v7, v2, v3
	v_lshlrev_b32_e32 v10, 3, v7
	v_ashrrev_i32_e32 v11, 31, v10
	v_cmp_gt_i32_e32 vcc, s93, v5
	v_lshlrev_b64 v[32:33], 1, v[10:11]
	v_mov_b64_e32 v[2:3], s[70:71]
	v_cndmask_b32_e32 v10, v214, v219, vcc
	v_add_u32_e32 v10, v10, v5
	v_mul_hi_i32 v11, v10, s55
	v_lshrrev_b32_e32 v12, 31, v11
	v_ashrrev_i32_e32 v11, 1, v11
	v_add_u32_e32 v181, v11, v12
	v_mul_lo_u32 v11, v181, 12
	v_sub_u32_e32 v44, v10, v11
	v_lshlrev_b32_e32 v12, 3, v44
	v_ashrrev_i32_e32 v13, 31, v12
	v_mad_i64_i32 v[10:11], s[4:5], v181, s47, v[2:3]
	v_lshlrev_b64 v[34:35], 1, v[12:13]
	v_lshl_add_u64 v[16:17], v[10:11], 0, v[34:35]
	v_mov_b64_e32 v[10:11], s[44:45]
	v_mad_i64_i32 v[36:37], s[4:5], v45, s95, v[10:11]
	v_lshlrev_b32_e32 v10, 4, v5
	v_add_u32_e32 v18, s76, v180
	v_add_u32_e32 v24, s76, v181
	v_add_u32_e32 v40, s77, v180
	v_add_u32_e32 v42, s77, v181
	v_mad_i64_i32 v[8:9], s[4:5], v180, s47, v[2:3]
	v_and_b32_e32 v38, 0x70, v10
	v_mov_b32_e32 v39, v1
	v_mad_i64_i32 v[18:19], s[4:5], v18, s47, v[2:3]
	v_mad_i64_i32 v[24:25], s[4:5], v24, s47, v[2:3]
	v_lshl_add_u64 v[26:27], v[36:37], 0, s[90:91]
	v_mad_i64_i32 v[40:41], s[4:5], v40, s47, v[2:3]
	v_mad_i64_i32 v[42:43], s[4:5], v42, s47, v[2:3]
	v_lshl_add_u64 v[8:9], v[8:9], 0, v[32:33]
	v_lshl_add_u64 v[20:21], v[18:19], 0, v[32:33]
	v_lshl_add_u64 v[24:25], v[24:25], 0, v[34:35]
	v_lshl_add_u64 v[28:29], v[26:27], 0, v[38:39]
	v_lshl_add_u64 v[40:41], v[40:41], 0, v[32:33]
	v_lshl_add_u64 v[42:43], v[42:43], 0, v[34:35]
	s_lshl_b32 s90, s77, 1
	v_lshl_add_u64 v[148:149], v[36:37], 0, v[38:39]
	global_load_dwordx4 v[8:11], v[8:9], off
	s_nop 0
	global_load_dwordx4 v[12:15], v[148:149], off
	s_nop 0
	global_load_dwordx4 v[16:19], v[16:17], off
	s_nop 0
	global_load_dwordx4 v[20:23], v[20:21], off
	s_nop 0
	global_load_dwordx4 v[24:27], v[24:25], off
	s_nop 0
	global_load_dwordx4 v[28:31], v[28:29], off
	s_nop 0
	global_load_dwordx4 v[108:111], v[40:41], off
	global_load_dwordx4 v[104:107], v[42:43], off
	v_lshl_add_u64 v[40:41], v[36:37], 0, s[90:91]
	v_add_u32_e32 v42, s50, v180
	v_lshl_add_u64 v[40:41], v[40:41], 0, v[38:39]
	v_mad_i64_i32 v[42:43], s[4:5], v42, s47, v[2:3]
	v_lshl_add_u64 v[42:43], v[42:43], 0, v[32:33]
	global_load_dwordx4 v[112:115], v[40:41], off
	global_load_dwordx4 v[116:119], v[42:43], off
	v_add_u32_e32 v40, s50, v181
	v_mad_i64_i32 v[2:3], s[4:5], v40, s47, v[2:3]
	s_lshl_b32 s90, s50, 1
	v_lshl_add_u64 v[2:3], v[2:3], 0, v[34:35]
	v_lshl_add_u64 v[36:37], v[36:37], 0, s[90:91]
	v_lshl_add_u64 v[36:37], v[36:37], 0, v[38:39]
	global_load_dwordx4 v[120:123], v[2:3], off
	global_load_dwordx4 v[124:127], v[36:37], off
	v_and_b32_e32 v2, 19, v5
	v_lshlrev_b32_e32 v3, 1, v5
	v_lshrrev_b32_e32 v5, 1, v5
	v_lshlrev_b32_e32 v150, 3, v6
	v_and_b32_e32 v3, 8, v3
	v_and_b32_e32 v5, 4, v5
	v_mul_lo_u32 v182, v180, s89
	v_lshlrev_b32_e32 v183, 4, v7
	v_mul_lo_u32 v184, v181, s89
	v_lshlrev_b32_e32 v185, 4, v44
	v_mul_lo_u32 v6, v45, s54
	v_or3_b32 v2, v2, v3, v5
	v_add3_u32 v3, 0, v182, v183
	v_add3_u32 v5, 0, v184, v185
	v_add3_u32 v186, 0, v6, v38
	v_mul_u32_u24_e32 v2, 0xd0, v2
	s_or_b64 s[40:41], s[72:73], s[2:3]
	v_lshl_add_u64 v[152:153], s[70:71], 0, v[32:33]
	v_lshl_add_u64 v[166:167], s[70:71], 0, v[34:35]
	v_add3_u32 v188, 0, v2, v0
	v_mov_b32_e32 v2, v1
	v_mov_b32_e32 v6, v1
	v_mov_b32_e32 v7, v1
	v_mov_b32_e32 v187, 0xf149f2ca
	s_xor_b64 s[68:69], s[40:41], -1
	s_or_b32 s36, s21, 31
	s_mov_b32 s37, 0
	v_mov_b32_e32 v169, 0xf149f2ca
	v_mov_b32_e32 v192, 0
	v_mov_b32_e32 v193, 0
	v_mov_b32_e32 v194, 0
	v_mov_b32_e32 v195, 0
	v_mov_b32_e32 v196, 0
	v_mov_b32_e32 v197, 0
	v_mov_b32_e32 v198, 0
	v_mov_b32_e32 v199, 0
	v_mov_b32_e32 v200, 0
	v_mov_b32_e32 v201, 0
	v_mov_b32_e32 v202, 0
	v_mov_b32_e32 v203, 0
	v_mov_b32_e32 v204, 0
	v_mov_b32_e32 v205, 0
	v_mov_b32_e32 v206, 0
	v_mov_b32_e32 v207, 0
	v_mov_b32_e32 v190, 0
	s_mov_b32 s42, 63
	s_waitcnt vmcnt(11)
	ds_write_b128 v3, v[8:11]
	s_waitcnt vmcnt(9)
	ds_write_b128 v5, v[16:19]
	ds_write_b128 v186, v[12:15] offset:53248
	s_waitcnt vmcnt(8)
	ds_write_b128 v3, v[20:23] offset:13312
	s_waitcnt vmcnt(7)
	ds_write_b128 v5, v[24:27] offset:13312
	s_waitcnt vmcnt(6)
	ds_write_b128 v186, v[28:31] offset:62464
	v_mul_u32_u24_e32 v3, 0x90, v4
	v_mov_b32_e32 v14, v1
	v_mov_b32_e32 v15, v1
	v_add3_u32 v189, 0, v3, v0
	v_mov_b32_e32 v0, v1
	v_mov_b32_e32 v3, v1
	v_mov_b32_e32 v4, v1
	v_mov_b32_e32 v5, v1
	v_mov_b32_e32 v8, v1
	v_mov_b32_e32 v9, v1
	v_mov_b32_e32 v10, v1
	v_mov_b32_e32 v11, v1
	v_mov_b32_e32 v12, v1
	v_mov_b32_e32 v13, v1
	v_mov_b64_e32 v[30:31], v[14:15]
	v_mov_b64_e32 v[46:47], v[14:15]
	v_mov_b64_e32 v[28:29], v[12:13]
	v_mov_b64_e32 v[26:27], v[10:11]
	v_mov_b64_e32 v[24:25], v[8:9]
	v_mov_b64_e32 v[22:23], v[6:7]
	v_mov_b64_e32 v[20:21], v[4:5]
	v_mov_b64_e32 v[18:19], v[2:3]
	v_mov_b64_e32 v[16:17], v[0:1]
	v_mov_b64_e32 v[44:45], v[12:13]
	v_mov_b64_e32 v[42:43], v[10:11]
	v_mov_b64_e32 v[40:41], v[8:9]
	v_mov_b64_e32 v[38:39], v[6:7]
	v_mov_b64_e32 v[36:37], v[4:5]
	v_mov_b64_e32 v[34:35], v[2:3]
	v_mov_b64_e32 v[32:33], v[0:1]
	s_waitcnt lgkmcnt(0)
	s_barrier
	s_branch .LBB0_1309

; #define LAS __attribute__((address_space(3)))
; template <int MODE, bool lookup, int MK>
; __device__ __forceinline__ void softmax_pv(f32x16& s0, f32x16& s1, SM& st, float boff, ldsp_t vb, LAS const float* tab, int t, int e_q, int posq, int hh, int r, bool mask_rt, float negv) {
;     ...
;   if (need_mask) {
; #pragma unroll
;     for (int i = 0; i < 16; ++i) { const int ek0 = ekb + (i & 7) + 16 * (i >> 3), ek1 = ek0 + 32;
;       const bool v0 = (ek0 <= e_q) && (ek0 < klim) && (MODE != 2 || t == 0 || (e_q - ek0 < 128));
;       const bool v1 = (ek1 <= e_q) && (ek1 < klim) && (MODE != 2 || t == 0 || (e_q - ek1 < 128));
;       s0[i] = v0 ? s0[i] : negv; s1[i] = v1 ? s1[i] : negv; }
;   }
; template <int MODE>
; __device__ __forceinline__ void attn_item(const Params& P, int layer, int b, int h, int map, int qb) {
;     ...
;   auto skipf = [&](int t) { bool sk = !active; if (t > 0) { if (64 * t > eq0 + 31) sk = true; if (MODE == 2 && eq0 - (64 * t + 63) >= 128) sk = true; } return sk; };
;   const int pr = (r & 0x13) | ((r & 4) << 1) | ((r & 8) >> 1);
;   auto lookf = [&](int t) { return MODE != 0 && (t == 0 || MODE == 2 || (eq0 - (64 * t + 63) < 128)); };
;   auto qk = [&](f32x16& s0, f32x16& s1, float& boff, int bufi, int t) {
;     const ldsp_t kbuf = lds + bufi * KBUF;
;     __builtin_amdgcn_s_setprio(1);
;     boff = sa.m > -1e29f ? sa.m : 0.f;
;     const float init = ((MODE == 1 && !lookf(t)) ? cfar : 0.f) - boff;
; #pragma unroll
;     for (int q = 0; q < 16; ++q) { s0[q] = init; s1[q] = init; }
; #pragma unroll
;     for (int s = 0; s < NST; ++s) {
;       const bf16x8 a0 = *(LAS const bf16x8*)(kbuf + pr * KSTR + s * 32 + hh * 16);
;       const bf16x8 a1 = *(LAS const bf16x8*)(kbuf + (32 + pr) * KSTR + s * 32 + hh * 16);
;       s0 = __builtin_amdgcn_mfma_f32_32x32x16_bf16(a0, qf[s], s0, 0, 0, 0);
;       s1 = __builtin_amdgcn_mfma_f32_32x32x16_bf16(a1, qf[s], s1, 0, 0, 0);
;     }
.LBB0_1309:
	s_and_b32 s43, s37, 2
	s_cmp_ge_u32 s37, s62
	s_cbranch_scc1 .LBB0_1316
	s_sub_i32 s2, s42, 63
	s_cmp_gt_i32 s2, s36
	s_cselect_b64 s[2:3], -1, 0
	s_or_b64 s[2:3], s[2:3], s[68:69]
	s_cmp_eq_u32 s37, 0
	s_cselect_b64 s[6:7], s[68:69], s[2:3]
	s_cselect_b64 s[2:3], -1, 0
	s_and_b64 vcc, exec, s[6:7]
	s_cbranch_vccnz .LBB0_1316
	s_cmp_gt_i32 s42, s21
	s_cselect_b64 s[4:5], -1, 0
	s_or_b64 s[4:5], s[2:3], s[4:5]
	s_setprio 1
	s_mul_i32 s6, s43, 0x3400
	v_add_u32_e32 v0, s6, v188
	ds_read_b128 v[6:9], v0
	ds_read_b128 v[2:5], v0 offset:6656
	ds_read_b128 v[10:13], v0 offset:32
	ds_read_b128 v[128:131], v0 offset:6688
	ds_read_b128 v[132:135], v0 offset:64
	ds_read_b128 v[136:139], v0 offset:6720
	ds_read_b128 v[140:143], v0 offset:96
	ds_read_b128 v[144:147], v0 offset:6752
	ds_read_b128 v[232:235], v0 offset:128
	ds_read_b128 v[236:239], v0 offset:6784
	ds_read_b128 v[240:243], v0 offset:160
	ds_read_b128 v[244:247], v0 offset:6816
	v_cmp_lt_f32_e32 vcc, s87, v169
	s_nop 1
	v_cndmask_b32_e32 v168, 0, v169, vcc
	s_waitcnt lgkmcnt(11)
	s_nop 0
	v_mfma_f32_32x32x16_bf16 v[64:79], v[6:9], v[84:87], v[192:207]
	s_waitcnt lgkmcnt(10)
	v_mfma_f32_32x32x16_bf16 v[48:63], v[2:5], v[84:87], v[192:207]
	s_waitcnt lgkmcnt(9)
	v_mfma_f32_32x32x16_bf16 v[64:79], v[10:13], v[80:83], v[64:79]
	s_waitcnt lgkmcnt(8)
	v_mfma_f32_32x32x16_bf16 v[48:63], v[128:131], v[80:83], v[48:63]
	s_waitcnt lgkmcnt(7)
	v_mfma_f32_32x32x16_bf16 v[64:79], v[132:135], v[92:95], v[64:79]
	s_waitcnt lgkmcnt(6)
	v_mfma_f32_32x32x16_bf16 v[48:63], v[136:139], v[92:95], v[48:63]
	s_waitcnt lgkmcnt(5)
	v_mfma_f32_32x32x16_bf16 v[64:79], v[140:143], v[88:91], v[64:79]
	s_waitcnt lgkmcnt(4)
	v_mfma_f32_32x32x16_bf16 v[48:63], v[144:147], v[88:91], v[48:63]
	s_waitcnt lgkmcnt(3)
	v_mfma_f32_32x32x16_bf16 v[64:79], v[232:235], v[100:103], v[64:79]
	s_waitcnt lgkmcnt(2)
	v_mfma_f32_32x32x16_bf16 v[48:63], v[236:239], v[100:103], v[48:63]
	s_waitcnt lgkmcnt(1)
	v_mfma_f32_32x32x16_bf16 v[64:79], v[240:243], v[96:99], v[64:79]
	s_waitcnt lgkmcnt(0)
	v_mfma_f32_32x32x16_bf16 v[48:63], v[244:247], v[96:99], v[48:63]
	s_setprio 0
	s_andn2_b64 vcc, exec, s[4:5]
	s_cbranch_vccnz .LBB0_1313
	s_and_b64 s[2:3], s[2:3], exec
	v_add_u32_e32 v0, s42, v150
	s_cselect_b32 s48, 16, 0x7fffffff
	v_subrev_u32_e32 v2, 63, v0
	v_subrev_u32_e32 v3, 31, v0
	v_cmp_le_i32_e32 vcc, v2, v151
	v_cmp_gt_u32_e64 s[2:3], s48, v2
	s_and_b64 vcc, vcc, s[2:3]
	v_cmp_le_i32_e64 s[2:3], v3, v151
	v_cmp_gt_u32_e64 s[4:5], s48, v3
	s_and_b64 s[2:3], s[2:3], s[4:5]
	v_subrev_u32_e32 v3, 62, v0
	v_cndmask_b32_e32 v64, v187, v64, vcc
	v_cndmask_b32_e64 v48, v187, v48, s[2:3]
	v_subrev_u32_e32 v4, 30, v0
	v_cmp_lt_i32_e32 vcc, v2, v151
	v_cmp_gt_u32_e64 s[2:3], s48, v3
	s_and_b64 vcc, vcc, s[2:3]
	v_cmp_le_i32_e64 s[2:3], v4, v151
	v_cmp_gt_u32_e64 s[4:5], s48, v4
	s_and_b64 s[2:3], s[2:3], s[4:5]
	v_subrev_u32_e32 v2, 61, v0
	v_cndmask_b32_e32 v65, v187, v65, vcc
	v_cndmask_b32_e64 v49, v187, v49, s[2:3]
	v_subrev_u32_e32 v3, 29, v0
	v_cmp_le_i32_e32 vcc, v2, v151
	v_cmp_gt_u32_e64 s[2:3], s48, v2
	s_and_b64 vcc, vcc, s[2:3]
	v_cmp_le_i32_e64 s[2:3], v3, v151
	v_cmp_gt_u32_e64 s[4:5], s48, v3
	s_and_b64 s[2:3], s[2:3], s[4:5]
	v_subrev_u32_e32 v2, 60, v0
	v_cndmask_b32_e32 v66, v187, v66, vcc
	v_cndmask_b32_e64 v50, v187, v50, s[2:3]
	v_subrev_u32_e32 v3, 28, v0
	v_cmp_le_i32_e32 vcc, v2, v151
	v_cmp_gt_u32_e64 s[2:3], s48, v2
	s_and_b64 vcc, vcc, s[2:3]
	v_cmp_le_i32_e64 s[2:3], v3, v151
	v_cmp_gt_u32_e64 s[4:5], s48, v3
	s_and_b64 s[2:3], s[2:3], s[4:5]
	v_subrev_u32_e32 v2, 59, v0
	v_cndmask_b32_e32 v67, v187, v67, vcc
	v_cndmask_b32_e64 v51, v187, v51, s[2:3]
	v_subrev_u32_e32 v3, 27, v0
	v_cmp_le_i32_e32 vcc, v2, v151
	v_cmp_gt_u32_e64 s[2:3], s48, v2
	s_and_b64 vcc, vcc, s[2:3]
	v_cmp_le_i32_e64 s[2:3], v3, v151
	v_cmp_gt_u32_e64 s[4:5], s48, v3
	s_and_b64 s[2:3], s[2:3], s[4:5]
	v_subrev_u32_e32 v2, 58, v0
	v_cndmask_b32_e32 v68, v187, v68, vcc
	v_cndmask_b32_e64 v52, v187, v52, s[2:3]
	v_subrev_u32_e32 v3, 26, v0
	v_cmp_le_i32_e32 vcc, v2, v151
	v_cmp_gt_u32_e64 s[2:3], s48, v2
	s_and_b64 vcc, vcc, s[2:3]
	v_cmp_le_i32_e64 s[2:3], v3, v151
	v_cmp_gt_u32_e64 s[4:5], s48, v3
	s_and_b64 s[2:3], s[2:3], s[4:5]
	v_subrev_u32_e32 v2, 57, v0
	v_cndmask_b32_e32 v69, v187, v69, vcc
	v_cndmask_b32_e64 v53, v187, v53, s[2:3]
	v_subrev_u32_e32 v3, 25, v0
	v_cmp_le_i32_e32 vcc, v2, v151
	v_cmp_gt_u32_e64 s[2:3], s48, v2
	s_and_b64 vcc, vcc, s[2:3]
	v_cmp_le_i32_e64 s[2:3], v3, v151
	v_cmp_gt_u32_e64 s[4:5], s48, v3
	s_and_b64 s[2:3], s[2:3], s[4:5]
	v_subrev_u32_e32 v2, 56, v0
	v_cndmask_b32_e32 v70, v187, v70, vcc
	v_cndmask_b32_e64 v54, v187, v54, s[2:3]
	v_subrev_u32_e32 v3, 24, v0
	v_cmp_le_i32_e32 vcc, v2, v151
	v_cmp_gt_u32_e64 s[2:3], s48, v2
	s_and_b64 vcc, vcc, s[2:3]
	v_cmp_le_i32_e64 s[2:3], v3, v151
	v_cmp_gt_u32_e64 s[4:5], s48, v3
	s_and_b64 s[2:3], s[2:3], s[4:5]
	v_subrev_u32_e32 v2, 47, v0
	v_cndmask_b32_e32 v71, v187, v71, vcc
	v_cndmask_b32_e64 v55, v187, v55, s[2:3]
	v_add_u32_e32 v3, -15, v0
	v_cmp_le_i32_e32 vcc, v2, v151
	v_cmp_gt_u32_e64 s[2:3], s48, v2
	s_and_b64 vcc, vcc, s[2:3]
	v_cmp_le_i32_e64 s[2:3], v3, v151
	v_cmp_gt_u32_e64 s[4:5], s48, v3
	s_and_b64 s[2:3], s[2:3], s[4:5]
	v_subrev_u32_e32 v2, 46, v0
	v_cndmask_b32_e32 v72, v187, v72, vcc
	v_cndmask_b32_e64 v56, v187, v56, s[2:3]
	v_add_u32_e32 v3, -14, v0
	v_cmp_le_i32_e32 vcc, v2, v151
	v_cmp_gt_u32_e64 s[2:3], s48, v2
	s_and_b64 vcc, vcc, s[2:3]
	v_cmp_le_i32_e64 s[2:3], v3, v151
	v_cmp_gt_u32_e64 s[4:5], s48, v3
	s_and_b64 s[2:3], s[2:3], s[4:5]
	v_subrev_u32_e32 v2, 45, v0
	v_cndmask_b32_e32 v73, v187, v73, vcc
; #define LAS __attribute__((address_space(3)))
; __device__ __forceinline__ float max32(float v) { return __builtin_fmaxf(v, xhalf(v)); }
; __device__ __forceinline__ float max3f(float a, float b, float c) { return __builtin_fmaxf(__builtin_fmaxf(a, b), c); }
; __device__ __forceinline__ void softmax_tile(f32x16& s0, f32x16& s1, SM& st, float boff, ldsp_t vb, int hh, int r) {
;   bf16x8 va0[2][2], va1[2][2];
; #pragma unroll
;   for (int kb = 0; kb < 2; ++kb)
; #pragma unroll
;     for (int s2 = 0; s2 < 2; ++s2) {
;       va0[kb][s2] = *(LAS const bf16x8*)(vb + r * 144 + (kb * 32 + s2 * 16 + hh * 8) * 2);
;       va1[kb][s2] = *(LAS const bf16x8*)(vb + (32 + r) * 144 + (kb * 32 + s2 * 16 + hh * 8) * 2);
;     }
;   float zmax = max3f(s0[0], s0[1], s0[2]);
; #pragma unroll
;   for (int k = 0; k < 6; ++k) zmax = max3f(zmax, s0[3 + 2 * k], s0[4 + 2 * k]);
;   zmax = max3f(zmax, s0[15], s1[0]);
; #pragma unroll
;   for (int k = 0; k < 7; ++k) zmax = max3f(zmax, s1[1 + 2 * k], s1[2 + 2 * k]);
;   zmax = fmaxf(zmax, s1[15]);
; #pragma unroll
;   for (int i = 0; i < 16; ++i) { s0[i] = __builtin_amdgcn_exp2f(s0[i]); s1[i] = __builtin_amdgcn_exp2f(s1[i]); }
;   if (__any((zmax + boff > st.m + DEFER_THR) || (st.m != boff))) {
;     const float zt = max32(zmax) + boff; const bool need = zt > st.m + DEFER_THR;
;     const float mn = need ? zt : st.m, alpha = __builtin_amdgcn_exp2f(st.m - mn), f = __builtin_amdgcn_exp2f(__builtin_fminf(boff - mn, 120.f)); st.m = mn;
; #pragma unroll
;     for (int i = 0; i < 16; ++i) { s0[i] *= f; s1[i] *= f; st.o0[i] *= alpha; st.o1[i] *= alpha; }
;     st.l *= alpha;
; template <int MODE, bool lookup, int MK>
; __device__ __forceinline__ void softmax_pv(f32x16& s0, f32x16& s1, SM& st, float boff, ldsp_t vb, LAS const float* tab, int t, int e_q, int posq, int hh, int r, bool mask_rt, float negv) {
;     ...
;   if (need_mask) {
; #pragma unroll
;     for (int i = 0; i < 16; ++i) { const int ek0 = ekb + (i & 7) + 16 * (i >> 3), ek1 = ek0 + 32;
;       const bool v0 = (ek0 <= e_q) && (ek0 < klim) && (MODE != 2 || t == 0 || (e_q - ek0 < 128));
;       const bool v1 = (ek1 <= e_q) && (ek1 < klim) && (MODE != 2 || t == 0 || (e_q - ek1 < 128));
;       s0[i] = v0 ? s0[i] : negv; s1[i] = v1 ? s1[i] : negv; }
;   }
	v_cndmask_b32_e64 v57, v187, v57, s[2:3]
	v_add_u32_e32 v3, -13, v0
	v_cmp_le_i32_e32 vcc, v2, v151
	v_cmp_gt_u32_e64 s[2:3], s48, v2
	s_and_b64 vcc, vcc, s[2:3]
	v_cmp_le_i32_e64 s[2:3], v3, v151
	v_cmp_gt_u32_e64 s[4:5], s48, v3
	s_and_b64 s[2:3], s[2:3], s[4:5]
	v_subrev_u32_e32 v2, 44, v0
	v_cndmask_b32_e32 v74, v187, v74, vcc
	v_cndmask_b32_e64 v58, v187, v58, s[2:3]
	v_add_u32_e32 v3, -12, v0
	v_cmp_le_i32_e32 vcc, v2, v151
	v_cmp_gt_u32_e64 s[2:3], s48, v2
	s_and_b64 vcc, vcc, s[2:3]
	v_cmp_le_i32_e64 s[2:3], v3, v151
	v_cmp_gt_u32_e64 s[4:5], s48, v3
	s_and_b64 s[2:3], s[2:3], s[4:5]
	v_subrev_u32_e32 v2, 43, v0
	v_cndmask_b32_e32 v75, v187, v75, vcc
	v_cndmask_b32_e64 v59, v187, v59, s[2:3]
	v_add_u32_e32 v3, -11, v0
	v_cmp_le_i32_e32 vcc, v2, v151
	v_cmp_gt_u32_e64 s[2:3], s48, v2
	s_and_b64 vcc, vcc, s[2:3]
	v_cmp_le_i32_e64 s[2:3], v3, v151
	v_cmp_gt_u32_e64 s[4:5], s48, v3
	s_and_b64 s[2:3], s[2:3], s[4:5]
	v_subrev_u32_e32 v2, 42, v0
	v_cndmask_b32_e32 v76, v187, v76, vcc
	v_cndmask_b32_e64 v60, v187, v60, s[2:3]
	v_add_u32_e32 v3, -10, v0
	v_cmp_le_i32_e32 vcc, v2, v151
	v_cmp_gt_u32_e64 s[2:3], s48, v2
	s_and_b64 vcc, vcc, s[2:3]
	v_cmp_le_i32_e64 s[2:3], v3, v151
	v_cmp_gt_u32_e64 s[4:5], s48, v3
	s_and_b64 s[2:3], s[2:3], s[4:5]
	v_subrev_u32_e32 v2, 41, v0
	v_cndmask_b32_e32 v77, v187, v77, vcc
	v_cndmask_b32_e64 v61, v187, v61, s[2:3]
	v_add_u32_e32 v3, -9, v0
	v_cmp_le_i32_e32 vcc, v2, v151
	v_cmp_gt_u32_e64 s[2:3], s48, v2
	s_and_b64 vcc, vcc, s[2:3]
	v_cmp_le_i32_e64 s[2:3], v3, v151
	v_cmp_gt_u32_e64 s[4:5], s48, v3
	s_and_b64 s[2:3], s[2:3], s[4:5]
	v_subrev_u32_e32 v2, 40, v0
	v_cndmask_b32_e32 v78, v187, v78, vcc
	v_cndmask_b32_e64 v62, v187, v62, s[2:3]
	v_add_u32_e32 v0, -8, v0
	v_cmp_le_i32_e32 vcc, v2, v151
	v_cmp_gt_u32_e64 s[2:3], s48, v2
	s_and_b64 vcc, vcc, s[2:3]
	v_cmp_le_i32_e64 s[2:3], v0, v151
	v_cmp_gt_u32_e64 s[4:5], s48, v0
	s_and_b64 s[2:3], s[2:3], s[4:5]
	v_cndmask_b32_e32 v79, v187, v79, vcc
	v_cndmask_b32_e64 v63, v187, v63, s[2:3]
.LBB0_1313:
	s_mul_i32 s2, s43, 0x2400
	v_add_u32_e32 v0, s2, v189
	ds_read_b128 v[140:143], v0 offset:53248
	ds_read_b128 v[136:139], v0 offset:53280
	ds_read_b128 v[144:147], v0 offset:57856
	ds_read_b128 v[132:135], v0 offset:57888
	ds_read_b128 v[128:131], v0 offset:53312
	ds_read_b128 v[6:9], v0 offset:53344
	ds_read_b128 v[10:13], v0 offset:57920
	ds_read_b128 v[2:5], v0 offset:57952
	v_max_f32_e32 v0, v65, v65
	v_max_f32_e32 v14, v64, v64
	v_max_f32_e32 v0, v14, v0
	v_max3_f32 v0, v0, v66, v67
	v_max3_f32 v0, v0, v68, v69
	v_max3_f32 v0, v0, v70, v71
	v_max3_f32 v0, v0, v72, v73
	v_max3_f32 v0, v0, v74, v75
	v_max3_f32 v0, v0, v76, v77
	v_max3_f32 v0, v0, v78, v79
	v_max3_f32 v0, v0, v48, v49
	v_max3_f32 v0, v0, v50, v51
	v_max3_f32 v0, v0, v52, v53
	v_max3_f32 v0, v0, v54, v55
	v_max3_f32 v0, v0, v56, v57
	v_max3_f32 v0, v0, v58, v59
	v_max3_f32 v0, v0, v60, v61
	v_exp_f32_e32 v174, v64
	v_exp_f32_e32 v64, v48
	v_exp_f32_e32 v175, v65
	v_exp_f32_e32 v65, v49
	v_exp_f32_e32 v176, v66
	v_exp_f32_e32 v66, v50
	v_exp_f32_e32 v177, v67
	v_exp_f32_e32 v67, v51
	v_exp_f32_e32 v178, v68
	v_exp_f32_e32 v172, v52
	v_exp_f32_e32 v179, v69
	v_exp_f32_e32 v173, v53
	v_exp_f32_e32 v68, v70
	v_exp_f32_e32 v170, v54
	v_exp_f32_e32 v69, v71
	v_exp_f32_e32 v171, v55
	v_exp_f32_e32 v72, v72
	v_exp_f32_e32 v14, v56
	v_exp_f32_e32 v73, v73
	v_exp_f32_e32 v15, v57
	v_exp_f32_e32 v70, v74
	v_exp_f32_e32 v54, v58
	v_exp_f32_e32 v71, v75
	v_exp_f32_e32 v55, v59
	v_exp_f32_e32 v48, v76
	v_exp_f32_e32 v50, v60
	v_exp_f32_e32 v49, v77
	v_exp_f32_e32 v51, v61
	v_exp_f32_e32 v52, v78
	v_exp_f32_e32 v56, v62
	v_exp_f32_e32 v53, v79
	v_exp_f32_e32 v57, v63
	v_max3_f32 v156, v0, v62, v63
	v_pk_add_f32 v[58:59], v[168:169], v[156:157]
	v_cmp_neq_f32_e64 s[2:3], v169, v168
	v_cmp_gt_f32_e32 vcc, v58, v59
	s_or_b64 vcc, s[2:3], vcc
	s_cbranch_vccz .LBB0_1315
	v_mov_b32_e32 v0, v210
	v_max_f32_e32 v58, v156, v156
	v_lshlrev_b32_e32 v0, 2, v0
	v_xor_b32_e32 v0, 0x80, v0
	ds_bpermute_b32 v0, v0, v156
	s_waitcnt lgkmcnt(0)
	v_max_f32_e32 v0, v0, v0
	v_max_f32_e32 v0, v58, v0
	v_add_f32_e32 v0, v168, v0
	v_cmp_gt_f32_e32 vcc, v0, v59
	s_nop 1
	v_cndmask_b32_e32 v59, v169, v0, vcc
	v_sub_f32_e32 v0, v168, v59
	v_min_f32_e32 v0, 0x42f00000, v0
	v_sub_f32_e32 v58, v169, v59
	v_exp_f32_e32 v0, v0
	v_exp_f32_e32 v58, v58
	v_mov_b32_e32 v169, v59
	v_cmp_lt_f32_e32 vcc, s87, v59
	s_nop 1
	v_cndmask_b32_e32 v192, 0, v59, vcc
	v_sub_f32_e32 v192, 0, v192
	v_mov_b32_e32 v193, v192
	v_mov_b32_e32 v194, v192
	v_mov_b32_e32 v195, v192
	v_mov_b32_e32 v196, v192
	v_mov_b32_e32 v197, v192
	v_mov_b32_e32 v198, v192
	v_mov_b32_e32 v199, v192
	v_mov_b32_e32 v200, v192
	v_mov_b32_e32 v201, v192
	v_mov_b32_e32 v202, v192
	v_mov_b32_e32 v203, v192
	v_mov_b32_e32 v204, v192
	v_mov_b32_e32 v205, v192
	v_mov_b32_e32 v206, v192
	v_mov_b32_e32 v207, v192
	v_pk_mul_f32 v[52:53], v[52:53], v[0:1] op_sel_hi:[1,0]
	v_pk_mul_f32 v[48:49], v[48:49], v[0:1] op_sel_hi:[1,0]
	v_pk_mul_f32 v[70:71], v[70:71], v[0:1] op_sel_hi:[1,0]
	v_pk_mul_f32 v[72:73], v[72:73], v[0:1] op_sel_hi:[1,0]
	v_pk_mul_f32 v[68:69], v[68:69], v[0:1] op_sel_hi:[1,0]
	v_pk_mul_f32 v[178:179], v[178:179], v[0:1] op_sel_hi:[1,0]
	v_pk_mul_f32 v[176:177], v[176:177], v[0:1] op_sel_hi:[1,0]
	v_pk_mul_f32 v[174:175], v[174:175], v[0:1] op_sel_hi:[1,0]
	v_pk_mul_f32 v[56:57], v[56:57], v[0:1] op_sel_hi:[1,0]
	v_pk_mul_f32 v[50:51], v[50:51], v[0:1] op_sel_hi:[1,0]
	v_pk_mul_f32 v[54:55], v[54:55], v[0:1] op_sel_hi:[1,0]
	v_pk_mul_f32 v[14:15], v[14:15], v[0:1] op_sel_hi:[1,0]
	v_pk_mul_f32 v[170:171], v[170:171], v[0:1] op_sel_hi:[1,0]
	v_pk_mul_f32 v[172:173], v[172:173], v[0:1] op_sel_hi:[1,0]
	v_pk_mul_f32 v[66:67], v[66:67], v[0:1] op_sel_hi:[1,0]
	v_pk_mul_f32 v[64:65], v[64:65], v[0:1] op_sel_hi:[1,0]
	v_pk_mul_f32 v[46:47], v[46:47], v[58:59] op_sel_hi:[1,0]
	v_pk_mul_f32 v[44:45], v[44:45], v[58:59] op_sel_hi:[1,0]
	v_pk_mul_f32 v[42:43], v[42:43], v[58:59] op_sel_hi:[1,0]
	v_pk_mul_f32 v[40:41], v[40:41], v[58:59] op_sel_hi:[1,0]
	v_pk_mul_f32 v[38:39], v[38:39], v[58:59] op_sel_hi:[1,0]
	v_pk_mul_f32 v[36:37], v[36:37], v[58:59] op_sel_hi:[1,0]
	v_pk_mul_f32 v[34:35], v[34:35], v[58:59] op_sel_hi:[1,0]
	v_pk_mul_f32 v[32:33], v[32:33], v[58:59] op_sel_hi:[1,0]
	v_pk_mul_f32 v[30:31], v[30:31], v[58:59] op_sel_hi:[1,0]
	v_pk_mul_f32 v[28:29], v[28:29], v[58:59] op_sel_hi:[1,0]
	v_pk_mul_f32 v[26:27], v[26:27], v[58:59] op_sel_hi:[1,0]
	v_pk_mul_f32 v[24:25], v[24:25], v[58:59] op_sel_hi:[1,0]
	v_pk_mul_f32 v[22:23], v[22:23], v[58:59] op_sel_hi:[1,0]
	v_pk_mul_f32 v[20:21], v[20:21], v[58:59] op_sel_hi:[1,0]
	v_pk_mul_f32 v[18:19], v[18:19], v[58:59] op_sel_hi:[1,0]
	v_pk_mul_f32 v[16:17], v[16:17], v[58:59] op_sel_hi:[1,0]
	v_mul_f32_e32 v190, v190, v58

; #define LAS __attribute__((address_space(3)))
; template <int MODE>
; __device__ __forceinline__ void attn_item(const Params& P, int layer, int b, int h, int map, int qb) {
;     ...
;   auto qk = [&](f32x16& s0, f32x16& s1, float& boff, int bufi, int t) {
;     const ldsp_t kbuf = lds + bufi * KBUF;
;     __builtin_amdgcn_s_setprio(1);
;     boff = sa.m > -1e29f ? sa.m : 0.f;
;     const float init = ((MODE == 1 && !lookf(t)) ? cfar : 0.f) - boff;
; #pragma unroll
;     for (int q = 0; q < 16; ++q) { s0[q] = init; s1[q] = init; }
; #pragma unroll
;     for (int s = 0; s < NST; ++s) {
;       const bf16x8 a0 = *(LAS const bf16x8*)(kbuf + pr * KSTR + s * 32 + hh * 16);
;       const bf16x8 a1 = *(LAS const bf16x8*)(kbuf + (32 + pr) * KSTR + s * 32 + hh * 16);
;       s0 = __builtin_amdgcn_mfma_f32_32x32x16_bf16(a0, qf[s], s0, 0, 0, 0);
;       s1 = __builtin_amdgcn_mfma_f32_32x32x16_bf16(a1, qf[s], s1, 0, 0, 0);
;     }
.LBB0_1316:
	s_xor_b32 s2, s43, 2
	s_mul_i32 s3, s2, 0x3400
	s_add_i32 s3, s3, 0
	v_add3_u32 v0, s3, v182, v183
	s_waitcnt vmcnt(5)
	ds_write_b128 v0, v[108:111]
	v_add3_u32 v0, s3, v184, v185
	s_mulk_i32 s2, 0x2400
	s_waitcnt vmcnt(4)
	ds_write_b128 v0, v[104:107]
	v_add_u32_e32 v0, s2, v186
	s_add_i32 s2, s37, 4
	s_min_i32 s2, s2, s63
	s_lshl_b32 s90, s2, 6
	s_waitcnt vmcnt(3)
	ds_write_b128 v0, v[112:115] offset:53248
	v_add_u32_e32 v0, s90, v180
	v_mad_i64_i32 v[2:3], s[2:3], v0, s47, v[152:153]
	v_add_u32_e32 v0, s90, v181
	v_mad_i64_i32 v[4:5], s[2:3], v0, s47, v[166:167]
	global_load_dwordx4 v[108:111], v[2:3], off
	global_load_dwordx4 v[104:107], v[4:5], off
	v_lshl_add_u64 v[2:3], s[90:91], 1, v[148:149]
	global_load_dwordx4 v[112:115], v[2:3], off
	s_add_i32 s2, s37, 1
	s_cmp_ge_u32 s2, s62
	s_cbranch_scc1 .LBB0_1308
	s_add_i32 s2, s42, 1
	s_cmp_le_i32 s2, s36
	s_cselect_b64 s[2:3], -1, 0
	s_and_b64 s[2:3], s[2:3], s[40:41]
	s_andn2_b64 vcc, exec, s[2:3]
	s_cbranch_vccnz .LBB0_1308
	s_add_i32 s3, s42, 64
	s_or_b32 s2, s43, 1
	s_cmp_le_i32 s3, s21
	s_setprio 1
	s_mul_i32 s3, s2, 0x3400
	v_add_u32_e32 v0, s3, v188
	ds_read_b128 v[6:9], v0
	ds_read_b128 v[2:5], v0 offset:6656
	ds_read_b128 v[10:13], v0 offset:32
	ds_read_b128 v[128:131], v0 offset:6688
	ds_read_b128 v[132:135], v0 offset:64
	ds_read_b128 v[136:139], v0 offset:6720
	ds_read_b128 v[140:143], v0 offset:96
	ds_read_b128 v[144:147], v0 offset:6752
	ds_read_b128 v[232:235], v0 offset:128
	ds_read_b128 v[236:239], v0 offset:6784
	ds_read_b128 v[240:243], v0 offset:160
	ds_read_b128 v[244:247], v0 offset:6816
	v_cmp_lt_f32_e32 vcc, s87, v169
	s_nop 1
	v_cndmask_b32_e32 v168, 0, v169, vcc
	s_waitcnt lgkmcnt(11)
	s_nop 0
	v_mfma_f32_32x32x16_bf16 v[64:79], v[6:9], v[84:87], v[192:207]
	s_waitcnt lgkmcnt(10)
	v_mfma_f32_32x32x16_bf16 v[48:63], v[2:5], v[84:87], v[192:207]
	s_waitcnt lgkmcnt(9)
	v_mfma_f32_32x32x16_bf16 v[64:79], v[10:13], v[80:83], v[64:79]
	s_waitcnt lgkmcnt(8)
	v_mfma_f32_32x32x16_bf16 v[48:63], v[128:131], v[80:83], v[48:63]
	s_waitcnt lgkmcnt(7)
	v_mfma_f32_32x32x16_bf16 v[64:79], v[132:135], v[92:95], v[64:79]
	s_waitcnt lgkmcnt(6)
	v_mfma_f32_32x32x16_bf16 v[48:63], v[136:139], v[92:95], v[48:63]
	s_waitcnt lgkmcnt(5)
	v_mfma_f32_32x32x16_bf16 v[64:79], v[140:143], v[88:91], v[64:79]
	s_waitcnt lgkmcnt(4)
	v_mfma_f32_32x32x16_bf16 v[48:63], v[144:147], v[88:91], v[48:63]
	s_waitcnt lgkmcnt(3)
	v_mfma_f32_32x32x16_bf16 v[64:79], v[232:235], v[100:103], v[64:79]
	s_waitcnt lgkmcnt(2)
	v_mfma_f32_32x32x16_bf16 v[48:63], v[236:239], v[100:103], v[48:63]
	s_waitcnt lgkmcnt(1)
	v_mfma_f32_32x32x16_bf16 v[64:79], v[240:243], v[96:99], v[64:79]
	s_waitcnt lgkmcnt(0)
	v_mfma_f32_32x32x16_bf16 v[48:63], v[244:247], v[96:99], v[48:63]
	s_setprio 0
	s_cbranch_scc1 .LBB0_1320
	v_add_u32_e32 v0, s42, v150
	v_add_u32_e32 v2, 1, v0
	v_add_u32_e32 v3, 33, v0
	v_cmp_gt_i32_e32 vcc, v2, v151
	s_nop 4
	v_cndmask_b32_e32 v64, v64, v187, vcc
	v_cmp_gt_i32_e32 vcc, v3, v151
	v_add_u32_e32 v3, 34, v0
	s_nop 0
	v_cndmask_b32_e32 v48, v48, v187, vcc
	v_cmp_lt_i32_e32 vcc, v2, v151
	v_add_u32_e32 v2, 3, v0
	s_nop 0
	v_cndmask_b32_e32 v65, v187, v65, vcc
	v_cmp_gt_i32_e32 vcc, v3, v151
	v_add_u32_e32 v3, 35, v0
	s_nop 0
	v_cndmask_b32_e32 v49, v49, v187, vcc
	v_cmp_gt_i32_e32 vcc, v2, v151
	v_add_u32_e32 v2, 4, v0
	s_nop 0
	v_cndmask_b32_e32 v66, v66, v187, vcc
	v_cmp_gt_i32_e32 vcc, v3, v151
	v_add_u32_e32 v3, 36, v0
	s_nop 0
	v_cndmask_b32_e32 v50, v50, v187, vcc
	v_cmp_gt_i32_e32 vcc, v2, v151
	v_add_u32_e32 v2, 5, v0
	s_nop 0
	v_cndmask_b32_e32 v67, v67, v187, vcc
	v_cmp_gt_i32_e32 vcc, v3, v151
	v_add_u32_e32 v3, 37, v0
	s_nop 0
	v_cndmask_b32_e32 v51, v51, v187, vcc
	v_cmp_gt_i32_e32 vcc, v2, v151
	v_add_u32_e32 v2, 6, v0
	s_nop 0
	v_cndmask_b32_e32 v68, v68, v187, vcc
	v_cmp_gt_i32_e32 vcc, v3, v151
	v_add_u32_e32 v3, 38, v0
	s_nop 0
	v_cndmask_b32_e32 v52, v52, v187, vcc
	v_cmp_gt_i32_e32 vcc, v2, v151
	v_add_u32_e32 v2, 7, v0
	s_nop 0
	v_cndmask_b32_e32 v69, v69, v187, vcc
	v_cmp_gt_i32_e32 vcc, v3, v151
	v_add_u32_e32 v3, 39, v0
	s_nop 0
	v_cndmask_b32_e32 v53, v53, v187, vcc
	v_cmp_gt_i32_e32 vcc, v2, v151
	v_add_u32_e32 v2, 8, v0
	s_nop 0
	v_cndmask_b32_e32 v70, v70, v187, vcc
	v_cmp_gt_i32_e32 vcc, v3, v151
	v_add_u32_e32 v3, 40, v0
	s_nop 0
	v_cndmask_b32_e32 v54, v54, v187, vcc
	v_cmp_gt_i32_e32 vcc, v2, v151
	v_add_u32_e32 v2, 17, v0
	s_nop 0
	v_cndmask_b32_e32 v71, v71, v187, vcc
	v_cmp_gt_i32_e32 vcc, v3, v151
	v_add_u32_e32 v3, 49, v0
	s_nop 0
	v_cndmask_b32_e32 v55, v55, v187, vcc
	v_cmp_gt_i32_e32 vcc, v2, v151
	v_add_u32_e32 v2, 18, v0
	s_nop 0
	v_cndmask_b32_e32 v72, v72, v187, vcc
	v_cmp_gt_i32_e32 vcc, v3, v151
	v_add_u32_e32 v3, 50, v0
	s_nop 0
	v_cndmask_b32_e32 v56, v56, v187, vcc
	v_cmp_gt_i32_e32 vcc, v2, v151
	v_add_u32_e32 v2, 19, v0
	s_nop 0
	v_cndmask_b32_e32 v73, v73, v187, vcc
	v_cmp_gt_i32_e32 vcc, v3, v151
	v_add_u32_e32 v3, 51, v0
	s_nop 0
	v_cndmask_b32_e32 v57, v57, v187, vcc
	v_cmp_gt_i32_e32 vcc, v2, v151
	v_add_u32_e32 v2, 20, v0
	s_nop 0
	v_cndmask_b32_e32 v74, v74, v187, vcc
	v_cmp_gt_i32_e32 vcc, v3, v151
	v_add_u32_e32 v3, 52, v0
	s_nop 0
	v_cndmask_b32_e32 v58, v58, v187, vcc
	v_cmp_gt_i32_e32 vcc, v2, v151
	v_add_u32_e32 v2, 21, v0
	s_nop 0
	v_cndmask_b32_e32 v75, v75, v187, vcc
	v_cmp_gt_i32_e32 vcc, v3, v151
	v_add_u32_e32 v3, 53, v0
	s_nop 0
	v_cndmask_b32_e32 v59, v59, v187, vcc
	v_cmp_gt_i32_e32 vcc, v2, v151
	v_add_u32_e32 v2, 22, v0
	s_nop 0
	v_cndmask_b32_e32 v76, v76, v187, vcc
	v_cmp_gt_i32_e32 vcc, v3, v151
	v_add_u32_e32 v3, 54, v0
	s_nop 0
	v_cndmask_b32_e32 v60, v60, v187, vcc
	v_cmp_gt_i32_e32 vcc, v2, v151
	v_add_u32_e32 v2, 23, v0
	s_nop 0
	v_cndmask_b32_e32 v77, v77, v187, vcc
	v_cmp_gt_i32_e32 vcc, v3, v151
	v_add_u32_e32 v3, 55, v0
	s_nop 0
	v_cndmask_b32_e32 v61, v61, v187, vcc
	v_cmp_gt_i32_e32 vcc, v2, v151
	v_add_u32_e32 v2, 24, v0
	v_add_u32_e32 v0, 56, v0
	v_cndmask_b32_e32 v78, v78, v187, vcc
	v_cmp_gt_i32_e32 vcc, v3, v151
	s_nop 1
	v_cndmask_b32_e32 v62, v62, v187, vcc
	v_cmp_gt_i32_e32 vcc, v2, v151
	s_nop 1
	v_cndmask_b32_e32 v79, v79, v187, vcc
	v_cmp_gt_i32_e32 vcc, v0, v151
	s_nop 1
	v_cndmask_b32_e32 v63, v63, v187, vcc
; #define LAS __attribute__((address_space(3)))
; __device__ __forceinline__ float max32(float v) { return __builtin_fmaxf(v, xhalf(v)); }
; __device__ __forceinline__ float max3f(float a, float b, float c) { return __builtin_fmaxf(__builtin_fmaxf(a, b), c); }
; __device__ __forceinline__ void softmax_tile(f32x16& s0, f32x16& s1, SM& st, float boff, ldsp_t vb, int hh, int r) {
;   bf16x8 va0[2][2], va1[2][2];
; #pragma unroll
;   for (int kb = 0; kb < 2; ++kb)
; #pragma unroll
;     for (int s2 = 0; s2 < 2; ++s2) {
;       va0[kb][s2] = *(LAS const bf16x8*)(vb + r * 144 + (kb * 32 + s2 * 16 + hh * 8) * 2);
;       va1[kb][s2] = *(LAS const bf16x8*)(vb + (32 + r) * 144 + (kb * 32 + s2 * 16 + hh * 8) * 2);
;     }
;   float zmax = max3f(s0[0], s0[1], s0[2]);
; #pragma unroll
;   for (int k = 0; k < 6; ++k) zmax = max3f(zmax, s0[3 + 2 * k], s0[4 + 2 * k]);
;   zmax = max3f(zmax, s0[15], s1[0]);
; #pragma unroll
;   for (int k = 0; k < 7; ++k) zmax = max3f(zmax, s1[1 + 2 * k], s1[2 + 2 * k]);
;   zmax = fmaxf(zmax, s1[15]);
; #pragma unroll
;   for (int i = 0; i < 16; ++i) { s0[i] = __builtin_amdgcn_exp2f(s0[i]); s1[i] = __builtin_amdgcn_exp2f(s1[i]); }
;   if (__any((zmax + boff > st.m + DEFER_THR) || (st.m != boff))) {
;     const float zt = max32(zmax) + boff; const bool need = zt > st.m + DEFER_THR;
;     const float mn = need ? zt : st.m, alpha = __builtin_amdgcn_exp2f(st.m - mn), f = __builtin_amdgcn_exp2f(__builtin_fminf(boff - mn, 120.f)); st.m = mn;
; #pragma unroll
;     for (int i = 0; i < 16; ++i) { s0[i] *= f; s1[i] *= f; st.o0[i] *= alpha; st.o1[i] *= alpha; }
;     st.l *= alpha;
.LBB0_1320:
	s_mulk_i32 s2, 0x2400
	v_add_u32_e32 v0, s2, v189
	ds_read_b128 v[140:143], v0 offset:53248
	ds_read_b128 v[136:139], v0 offset:53280
	ds_read_b128 v[144:147], v0 offset:57856
	ds_read_b128 v[132:135], v0 offset:57888
	ds_read_b128 v[128:131], v0 offset:53312
	ds_read_b128 v[6:9], v0 offset:53344
	ds_read_b128 v[10:13], v0 offset:57920
	ds_read_b128 v[2:5], v0 offset:57952
	v_max_f32_e32 v0, v65, v65
	v_max_f32_e32 v14, v64, v64
	v_max_f32_e32 v0, v14, v0
	v_max3_f32 v0, v0, v66, v67
	v_max3_f32 v0, v0, v68, v69
	v_max3_f32 v0, v0, v70, v71
	v_max3_f32 v0, v0, v72, v73
	v_max3_f32 v0, v0, v74, v75
	v_max3_f32 v0, v0, v76, v77
	v_max3_f32 v0, v0, v78, v79
	v_max3_f32 v0, v0, v48, v49
	v_max3_f32 v0, v0, v50, v51
	v_max3_f32 v0, v0, v52, v53
	v_max3_f32 v0, v0, v54, v55
	v_max3_f32 v0, v0, v56, v57
	v_max3_f32 v0, v0, v58, v59
	v_max3_f32 v0, v0, v60, v61
	v_exp_f32_e32 v174, v64
	v_exp_f32_e32 v64, v48
	v_exp_f32_e32 v175, v65
	v_exp_f32_e32 v65, v49
	v_exp_f32_e32 v176, v66
	v_exp_f32_e32 v66, v50
	v_exp_f32_e32 v177, v67
	v_exp_f32_e32 v67, v51
	v_exp_f32_e32 v178, v68
	v_exp_f32_e32 v172, v52
	v_exp_f32_e32 v179, v69
	v_exp_f32_e32 v173, v53
	v_exp_f32_e32 v68, v70
	v_exp_f32_e32 v170, v54
	v_exp_f32_e32 v69, v71
	v_exp_f32_e32 v171, v55
	v_exp_f32_e32 v72, v72
	v_exp_f32_e32 v14, v56
	v_exp_f32_e32 v73, v73
	v_exp_f32_e32 v15, v57
	v_exp_f32_e32 v70, v74
	v_exp_f32_e32 v54, v58
	v_exp_f32_e32 v71, v75
	v_exp_f32_e32 v55, v59
	v_exp_f32_e32 v48, v76
	v_exp_f32_e32 v50, v60
	v_exp_f32_e32 v49, v77
	v_exp_f32_e32 v51, v61
	v_exp_f32_e32 v52, v78
	v_exp_f32_e32 v56, v62
	v_exp_f32_e32 v53, v79
	v_exp_f32_e32 v57, v63
	v_max3_f32 v156, v0, v62, v63
	v_pk_add_f32 v[58:59], v[168:169], v[156:157]
	v_cmp_neq_f32_e64 s[2:3], v169, v168
	v_cmp_gt_f32_e32 vcc, v58, v59
	s_or_b64 vcc, s[2:3], vcc
	s_cbranch_vccz .LBB0_1307
	v_mov_b32_e32 v0, v210
	v_max_f32_e32 v58, v156, v156
	v_lshlrev_b32_e32 v0, 2, v0
	v_xor_b32_e32 v0, 0x80, v0
	ds_bpermute_b32 v0, v0, v156
	s_waitcnt lgkmcnt(0)
	v_max_f32_e32 v0, v0, v0
	v_max_f32_e32 v0, v58, v0
	v_add_f32_e32 v0, v168, v0
	v_cmp_gt_f32_e32 vcc, v0, v59
	s_nop 1
	v_cndmask_b32_e32 v59, v169, v0, vcc
	v_sub_f32_e32 v0, v168, v59
	v_min_f32_e32 v0, 0x42f00000, v0
	v_sub_f32_e32 v58, v169, v59
	v_exp_f32_e32 v0, v0
	v_exp_f32_e32 v58, v58
	v_mov_b32_e32 v169, v59
	v_cmp_lt_f32_e32 vcc, s87, v59
	s_nop 1
	v_cndmask_b32_e32 v192, 0, v59, vcc
	v_sub_f32_e32 v192, 0, v192
	v_mov_b32_e32 v193, v192
	v_mov_b32_e32 v194, v192
	v_mov_b32_e32 v195, v192
	v_mov_b32_e32 v196, v192
	v_mov_b32_e32 v197, v192
	v_mov_b32_e32 v198, v192
	v_mov_b32_e32 v199, v192
	v_mov_b32_e32 v200, v192
	v_mov_b32_e32 v201, v192
	v_mov_b32_e32 v202, v192
	v_mov_b32_e32 v203, v192
	v_mov_b32_e32 v204, v192
	v_mov_b32_e32 v205, v192
	v_mov_b32_e32 v206, v192
	v_mov_b32_e32 v207, v192
	v_pk_mul_f32 v[52:53], v[52:53], v[0:1] op_sel_hi:[1,0]
	v_pk_mul_f32 v[48:49], v[48:49], v[0:1] op_sel_hi:[1,0]
	v_pk_mul_f32 v[70:71], v[70:71], v[0:1] op_sel_hi:[1,0]
	v_pk_mul_f32 v[72:73], v[72:73], v[0:1] op_sel_hi:[1,0]
	v_pk_mul_f32 v[68:69], v[68:69], v[0:1] op_sel_hi:[1,0]
	v_pk_mul_f32 v[178:179], v[178:179], v[0:1] op_sel_hi:[1,0]
	v_pk_mul_f32 v[176:177], v[176:177], v[0:1] op_sel_hi:[1,0]
	v_pk_mul_f32 v[174:175], v[174:175], v[0:1] op_sel_hi:[1,0]
	v_pk_mul_f32 v[56:57], v[56:57], v[0:1] op_sel_hi:[1,0]
	v_pk_mul_f32 v[50:51], v[50:51], v[0:1] op_sel_hi:[1,0]
	v_pk_mul_f32 v[54:55], v[54:55], v[0:1] op_sel_hi:[1,0]
	v_pk_mul_f32 v[14:15], v[14:15], v[0:1] op_sel_hi:[1,0]
	v_pk_mul_f32 v[170:171], v[170:171], v[0:1] op_sel_hi:[1,0]
	v_pk_mul_f32 v[172:173], v[172:173], v[0:1] op_sel_hi:[1,0]
	v_pk_mul_f32 v[66:67], v[66:67], v[0:1] op_sel_hi:[1,0]
	v_pk_mul_f32 v[64:65], v[64:65], v[0:1] op_sel_hi:[1,0]
	v_pk_mul_f32 v[46:47], v[46:47], v[58:59] op_sel_hi:[1,0]
	v_pk_mul_f32 v[44:45], v[44:45], v[58:59] op_sel_hi:[1,0]
	v_pk_mul_f32 v[42:43], v[42:43], v[58:59] op_sel_hi:[1,0]
	v_pk_mul_f32 v[40:41], v[40:41], v[58:59] op_sel_hi:[1,0]
	v_pk_mul_f32 v[38:39], v[38:39], v[58:59] op_sel_hi:[1,0]
	v_pk_mul_f32 v[36:37], v[36:37], v[58:59] op_sel_hi:[1,0]
	v_pk_mul_f32 v[34:35], v[34:35], v[58:59] op_sel_hi:[1,0]
	v_pk_mul_f32 v[32:33], v[32:33], v[58:59] op_sel_hi:[1,0]
	v_pk_mul_f32 v[30:31], v[30:31], v[58:59] op_sel_hi:[1,0]
	v_pk_mul_f32 v[28:29], v[28:29], v[58:59] op_sel_hi:[1,0]
	v_pk_mul_f32 v[26:27], v[26:27], v[58:59] op_sel_hi:[1,0]
	v_pk_mul_f32 v[24:25], v[24:25], v[58:59] op_sel_hi:[1,0]
	v_pk_mul_f32 v[22:23], v[22:23], v[58:59] op_sel_hi:[1,0]
	v_pk_mul_f32 v[20:21], v[20:21], v[58:59] op_sel_hi:[1,0]
	v_pk_mul_f32 v[18:19], v[18:19], v[58:59] op_sel_hi:[1,0]
	v_pk_mul_f32 v[16:17], v[16:17], v[58:59] op_sel_hi:[1,0]
	v_mul_f32_e32 v190, v190, v58
	s_branch .LBB0_1307
